# cand G with the prompt-prepass group reduction done per wave without the second workgroup barrier (partials double-buffered) + P1 epilogue rsm values loaded once before the stores
# speedup vs baseline: 1.0007x; 1.0007x over previous
.LBB0_806:
	s_or_b64 exec, exec, s[38:39]
	s_waitcnt lgkmcnt(0)
	s_barrier
	s_mov_b64 s[38:39], exec
	s_mov_b64 exec, 0xffff
	v_lshl_add_u32 v245, v236, 2, s85
	ds_read2_b32 v[134:135], v245 offset1:16
	ds_read2_b32 v[246:247], v245 offset0:32 offset1:48
	ds_read2_b32 v[248:249], v245 offset0:64 offset1:80
	ds_read2_b32 v[250:251], v245 offset0:96 offset1:112
	s_xor_b32 s85, s85, 0x400
	s_waitcnt lgkmcnt(3)
	v_add_f32_e32 v134, 0, v134
	v_add_f32_e32 v136, v134, v135
	v_lshl_add_u32 v135, v236, 2, s96
	s_waitcnt lgkmcnt(2)
	v_add_f32_e32 v134, v136, v246
	v_add_f32_e32 v136, v134, v247
	s_waitcnt lgkmcnt(1)
	v_add_f32_e32 v134, v136, v248
	v_add_f32_e32 v136, v134, v249
	s_waitcnt lgkmcnt(0)
	v_add_f32_e32 v134, v136, v250
	v_add_f32_e32 v134, v134, v251
	ds_write_b32 v135, v134
.LBB0_808:
	s_mov_b64 exec, s[38:39]
	s_waitcnt lgkmcnt(0)
	v_mov_b32_e32 v134, s96
	v_mov_b32_e32 v136, s93
	ds_read_b32 v135, v134
	ds_read_b32 v134, v136
	s_waitcnt vmcnt(14)
	v_lshlrev_b32_e32 v140, 16, v242
	v_add_f32_e32 v140, v110, v140
	v_mul_f32_e32 v140, 0xbfb8aa3b, v140
	v_pk_mul_f32 v[122:123], v[104:105], v[122:123]
	s_waitcnt lgkmcnt(0)
	v_pk_mul_f32 v[134:135], v[134:135], s[84:85] op_sel_hi:[1,0]
	v_pk_fma_f32 v[122:123], v[106:107], v[124:125], v[122:123]
	v_fma_f32 v136, -v135, v135, v134
	v_add_f32_e32 v136, 0x358637bd, v136
	v_mul_f32_e32 v137, 0x4b800000, v136
	v_cmp_gt_f32_e32 vcc, s33, v136
	v_pk_add_f32 v[134:135], v[142:143], v[134:135] op_sel:[0,1] neg_lo:[0,1] neg_hi:[0,1]
	v_exp_f32_e32 v142, v140
	v_cndmask_b32_e32 v136, v136, v137, vcc
	v_rsq_f32_e32 v136, v136
	s_waitcnt vmcnt(13)
	v_lshlrev_b32_e32 v140, 16, v241
	v_add_f32_e32 v140, v112, v140
	v_mul_f32_e32 v140, 0xbfb8aa3b, v140
	v_mul_f32_e32 v137, 0x45800000, v136
	v_cndmask_b32_e32 v136, v136, v137, vcc
	v_pk_mul_f32 v[134:135], v[134:135], v[136:137] op_sel_hi:[1,0]
	v_exp_f32_e32 v143, v140
	v_pk_fma_f32 v[136:137], v[100:101], v[134:135], v[102:103]
	v_add_f32_e32 v142, 1.0, v142
	v_mul_f32_e32 v134, 0xbfb8aa3b, v136
	v_mul_f32_e32 v135, 0xbfb8aa3b, v137
	v_exp_f32_e32 v134, v134
	v_exp_f32_e32 v135, v135
	v_mov_b32_e32 v145, v136
	v_and_b32_e32 v136, 0xffff0000, v241
	v_add_f32_e32 v134, 1.0, v134
	v_add_f32_e32 v135, 1.0, v135
	v_rcp_f32_e32 v139, v134
	v_rcp_f32_e32 v141, v135
	v_lshlrev_b32_e32 v134, 16, v238
	v_and_b32_e32 v135, 0xffff0000, v238
	v_pk_fma_f32 v[122:123], v[108:109], v[134:135], v[122:123]
	v_add_f32_e32 v136, v113, v136
	v_mov_b32_e32 v144, v122
	v_and_b32_e32 v122, 0xffff0000, v242
	v_add_f32_e32 v122, v111, v122
	v_mul_f32_e32 v122, 0xbfb8aa3b, v122
	v_add_f32_e32 v143, 1.0, v143
	v_exp_f32_e32 v122, v122
	v_mul_f32_e32 v136, 0xbfb8aa3b, v136
	v_rcp_f32_e32 v142, v142
	v_rcp_f32_e32 v143, v143
	v_exp_f32_e32 v136, v136
	v_lshlrev_b32_e32 v138, 16, v243
	v_pk_mul_f32 v[138:139], v[144:145], v[138:139]
	v_add_f32_e32 v122, 1.0, v122
	v_pk_mul_f32 v[138:139], v[138:139], v[142:143]
	v_rcp_f32_e32 v142, v122
	v_add_f32_e32 v122, 1.0, v136
	v_rcp_f32_e32 v143, v122
	v_and_b32_e32 v140, 0xffff0000, v243
	v_mov_b32_e32 v136, v123
	v_pk_mul_f32 v[122:123], v[136:137], v[140:141]
	s_add_u32 s18, s40, 0xffffe400
	v_pk_mul_f32 v[122:123], v[122:123], v[142:143]
	s_addc_u32 s19, s41, -1
	v_add_f32_e32 v122, v122, v123
	s_or_b64 s[38:39], s[82:83], s[18:19]
	v_add_f32_e32 v138, v138, v139
	v_cvt_pk_bf16_f32 v136, v138, v122
	v_lshl_add_u64 v[122:123], s[38:39], 1, v[116:117]
	global_store_dword v[122:123], v136, off
	s_and_b64 vcc, exec, s[86:87]
	v_mov_b32_e32 v122, v15
	s_cbranch_vccz .LBB0_817
	s_cmp_lt_i32 s97, 2
	s_mov_b64 s[44:45], -1
	s_cbranch_scc1 .LBB0_813
	s_cmp_eq_u32 s97, 2
	v_mov_b32_e32 v122, v229
	s_cbranch_scc0 .LBB0_812
	v_mov_b32_e32 v122, v9
